# fused epilogue second half: one wait for all residual loads, later counted waits (which drained stores) replaced by 2 wait-state nops
# speedup vs baseline: 1.0019x; 1.0019x over previous
; __device__ __forceinline__ uint4 pack8(const float* f) { uint4 o; o.x = pk2(f[0], f[1]); o.y = pk2(f[2], f[3]); o.z = pk2(f[4], f[5]); o.w = pk2(f[6], f[7]); return o; }
;     __device__ __forceinline__ void fused(f32x4 (&acc)[2][2][4][2], const pg8::Unit& u, int wr, int wc, int fr, int fq, LAS unsigned char* lds, int wid, int lane) const {
;     ...
;         for (int ai = 0; ai < 2; ++ai) {
;             if (ai == 1) {
; #pragma unroll
;                 for (int m = 0; m < 4; ++m)
; #pragma unroll
;                     for (int bj = 0; bj < 2; ++bj) xold[m][bj] = *(const uint4*)(XB + (size_t)(u.pm * 256 + 128 + wr * 64 + m * 16 + fr) * 1024 + cb + bj * 128);
;             }
; #pragma unroll
;             for (int m = 0; m < 4; ++m) {
;                 const int rl = ai * 128 + wr * 64 + m * 16 + fr; const size_t off = (size_t)(u.pm * 256 + rl) * 1024 + cb;
;                 const float rsf = S[rl]; float q = 0.f;
; #pragma unroll
;                 for (int bj = 0; bj < 2; ++bj) {
;                     float xo[8]; unpack8(xold[m][bj], xo);
;                     f32x4 v0 = acc[ai][bj][m][0] * rsf * g4[bj][0], v1 = acc[ai][bj][m][1] * rsf * g4[bj][1];
;                     float xn[8];
; #pragma unroll
;                     for (int e = 0; e < 4; ++e) { xn[e] = xo[e] + v0[e]; xn[4 + e] = xo[4 + e] + v1[e]; }
;                     if (outf) { *(f32x4*)(outf + off + bj * 128) = (f32x4){xn[0], xn[1], xn[2], xn[3]}; *(f32x4*)(outf + off + bj * 128 + 4) = (f32x4){xn[4], xn[5], xn[6], xn[7]}; }
;                     else { *(uint4*)(XB + off + bj * 128) = pack8(xn); }
.LBB0_647:
	s_or_b64 exec, exec, s[82:83]
	v_add_u32_e32 v5, s3, v175
	s_waitcnt lgkmcnt(0)
	v_add_u32_e32 v26, 0x80, v5
	v_ashrrev_i32_e32 v27, 31, v26
	v_add_u32_e32 v28, 0x90, v5
	v_lshlrev_b64 v[26:27], 11, v[26:27]
	v_ashrrev_i32_e32 v29, 31, v28
	v_lshl_add_u64 v[26:27], v[98:99], 0, v[26:27]
	v_lshlrev_b64 v[28:29], 11, v[28:29]
	v_lshl_add_u64 v[28:29], v[98:99], 0, v[28:29]
	global_load_dwordx4 v[50:53], v[26:27], off offset:256
	global_load_dwordx4 v[54:57], v[26:27], off
	global_load_dwordx4 v[46:49], v[28:29], off
	global_load_dwordx4 v[42:45], v[28:29], off offset:256
	v_add_u32_e32 v26, 0xa0, v5
	v_ashrrev_i32_e32 v27, 31, v26
	v_lshlrev_b64 v[26:27], 11, v[26:27]
	v_lshl_add_u64 v[26:27], v[98:99], 0, v[26:27]
	global_load_dwordx4 v[38:41], v[26:27], off
	global_load_dwordx4 v[34:37], v[26:27], off offset:256
	v_add_u32_e32 v26, 0xb0, v5
	v_ashrrev_i32_e32 v27, 31, v26
	v_lshlrev_b64 v[26:27], 11, v[26:27]
	v_lshl_add_u64 v[26:27], v[98:99], 0, v[26:27]
	global_load_dwordx4 v[30:33], v[26:27], off
	s_nop 0
	global_load_dwordx4 v[26:29], v[26:27], off offset:256
	ds_read_b32 v64, v224 offset:4608
	v_add_u32_e32 v58, s2, v233
	v_ashrrev_i32_e32 v59, 31, v58
	v_lshlrev_b64 v[62:63], 10, v[58:59]
	v_lshl_add_u64 v[134:135], v[62:63], 0, v[102:103]
	s_waitcnt lgkmcnt(0)
	v_pk_mul_f32 v[58:59], v[128:129], v[64:65] op_sel_hi:[1,0]
	v_pk_mul_f32 v[60:61], v[132:133], v[64:65] op_sel_hi:[1,0]
	v_pk_mul_f32 v[126:127], v[126:127], v[64:65] op_sel_hi:[1,0]
	v_pk_mul_f32 v[128:129], v[130:131], v[64:65] op_sel_hi:[1,0]
	s_mov_b64 s[82:83], -1
	s_and_b64 vcc, exec, s[8:9]
	s_waitcnt vmcnt(0)
	v_lshlrev_b32_e32 v130, 16, v54
	v_and_b32_e32 v131, 0xffff0000, v54
	v_lshlrev_b32_e32 v132, 16, v55
	v_and_b32_e32 v133, 0xffff0000, v55
	v_lshlrev_b32_e32 v54, 16, v56
	v_and_b32_e32 v55, 0xffff0000, v56
	v_lshlrev_b32_e32 v56, 16, v57
	v_and_b32_e32 v57, 0xffff0000, v57
	v_pk_fma_f32 v[58:59], v[22:23], v[58:59], v[130:131]
	v_pk_fma_f32 v[54:55], v[18:19], v[60:61], v[54:55]
	v_pk_fma_f32 v[60:61], v[24:25], v[126:127], v[132:133]
	v_pk_fma_f32 v[56:57], v[20:21], v[128:129], v[56:57]
	v_lshl_add_u64 v[128:129], v[134:135], 2, s[22:23]
	s_cbranch_vccnz .LBB0_649
	s_mov_b64 s[82:83], 0
	global_store_dwordx4 v[128:129], v[58:61], off
	global_store_dwordx4 v[128:129], v[54:57], off offset:16

; __device__ __forceinline__ uint4 pack8(const float* f) { uint4 o; o.x = pk2(f[0], f[1]); o.y = pk2(f[2], f[3]); o.z = pk2(f[4], f[5]); o.w = pk2(f[6], f[7]); return o; }
;     __device__ __forceinline__ void fused(f32x4 (&acc)[2][2][4][2], const pg8::Unit& u, int wr, int wc, int fr, int fq, LAS unsigned char* lds, int wid, int lane) const {
;     ...
;             for (int m = 0; m < 4; ++m) {
;                 const int rl = ai * 128 + wr * 64 + m * 16 + fr; const size_t off = (size_t)(u.pm * 256 + rl) * 1024 + cb;
;                 const float rsf = S[rl]; float q = 0.f;
; #pragma unroll
;                 for (int bj = 0; bj < 2; ++bj) {
;                     float xo[8]; unpack8(xold[m][bj], xo);
;                     f32x4 v0 = acc[ai][bj][m][0] * rsf * g4[bj][0], v1 = acc[ai][bj][m][1] * rsf * g4[bj][1];
;                     float xn[8];
; #pragma unroll
;                     for (int e = 0; e < 4; ++e) { xn[e] = xo[e] + v0[e]; xn[4 + e] = xo[4 + e] + v1[e]; }
;                     if (outf) { *(f32x4*)(outf + off + bj * 128) = (f32x4){xn[0], xn[1], xn[2], xn[3]}; *(f32x4*)(outf + off + bj * 128 + 4) = (f32x4){xn[4], xn[5], xn[6], xn[7]}; }
;                     else { *(uint4*)(XB + off + bj * 128) = pack8(xn); }
.LBB0_657:
	s_or_b64 exec, exec, s[82:83]
	ds_read_b32 v56, v224 offset:4672
	s_waitcnt lgkmcnt(1)
	v_add_u32_e32 v50, s2, v231
	v_ashrrev_i32_e32 v51, 31, v50
	v_lshlrev_b64 v[54:55], 10, v[50:51]
	s_nop 1
	v_lshlrev_b32_e32 v50, 16, v46
	v_and_b32_e32 v51, 0xffff0000, v46
	v_lshlrev_b32_e32 v52, 16, v47
	v_and_b32_e32 v53, 0xffff0000, v47
	v_lshlrev_b32_e32 v60, 16, v48
	v_and_b32_e32 v61, 0xffff0000, v48
	v_lshlrev_b32_e32 v62, 16, v49
	v_and_b32_e32 v63, 0xffff0000, v49
	s_waitcnt lgkmcnt(0)
	v_pk_mul_f32 v[46:47], v[114:115], v[56:57] op_sel_hi:[1,0]
	v_pk_mul_f32 v[48:49], v[116:117], v[56:57] op_sel_hi:[1,0]
	v_pk_fma_f32 v[46:47], v[22:23], v[46:47], v[50:51]
	v_pk_fma_f32 v[50:51], v[18:19], v[48:49], v[60:61]
	v_pk_mul_f32 v[48:49], v[110:111], v[56:57] op_sel_hi:[1,0]
	v_lshl_add_u64 v[58:59], v[54:55], 0, v[102:103]
	v_pk_fma_f32 v[48:49], v[24:25], v[48:49], v[52:53]
	v_pk_mul_f32 v[52:53], v[112:113], v[56:57] op_sel_hi:[1,0]
	s_mov_b64 s[82:83], -1
	v_pk_fma_f32 v[52:53], v[20:21], v[52:53], v[62:63]
	s_and_b64 vcc, exec, s[8:9]
	v_lshl_add_u64 v[60:61], v[58:59], 2, s[22:23]
	s_cbranch_vccnz .LBB0_659
	s_mov_b64 s[82:83], 0
	global_store_dwordx4 v[60:61], v[46:49], off
	global_store_dwordx4 v[60:61], v[50:53], off offset:16

; __device__ __forceinline__ uint4 pack8(const float* f) { uint4 o; o.x = pk2(f[0], f[1]); o.y = pk2(f[2], f[3]); o.z = pk2(f[4], f[5]); o.w = pk2(f[6], f[7]); return o; }
;     __device__ __forceinline__ void fused(f32x4 (&acc)[2][2][4][2], const pg8::Unit& u, int wr, int wc, int fr, int fq, LAS unsigned char* lds, int wid, int lane) const {
;     ...
;             for (int m = 0; m < 4; ++m) {
;                 const int rl = ai * 128 + wr * 64 + m * 16 + fr; const size_t off = (size_t)(u.pm * 256 + rl) * 1024 + cb;
;                 const float rsf = S[rl]; float q = 0.f;
; #pragma unroll
;                 for (int bj = 0; bj < 2; ++bj) {
;                     float xo[8]; unpack8(xold[m][bj], xo);
;                     f32x4 v0 = acc[ai][bj][m][0] * rsf * g4[bj][0], v1 = acc[ai][bj][m][1] * rsf * g4[bj][1];
;                     float xn[8];
; #pragma unroll
;                     for (int e = 0; e < 4; ++e) { xn[e] = xo[e] + v0[e]; xn[4 + e] = xo[4 + e] + v1[e]; }
;                     if (outf) { *(f32x4*)(outf + off + bj * 128) = (f32x4){xn[0], xn[1], xn[2], xn[3]}; *(f32x4*)(outf + off + bj * 128 + 4) = (f32x4){xn[4], xn[5], xn[6], xn[7]}; }
;                     else { *(uint4*)(XB + off + bj * 128) = pack8(xn); }
.LBB0_661:
	v_mov_b32_e32 v57, v56
	s_nop 1
	v_lshlrev_b32_e32 v54, 16, v42
	v_and_b32_e32 v55, 0xffff0000, v42
	v_lshlrev_b32_e32 v62, 16, v43
	v_and_b32_e32 v63, 0xffff0000, v43
	v_lshlrev_b32_e32 v64, 16, v44
	v_and_b32_e32 v65, 0xffff0000, v44
	v_lshlrev_b32_e32 v110, 16, v45
	v_and_b32_e32 v111, 0xffff0000, v45
	v_pk_mul_f32 v[42:43], v[106:107], v[56:57]
	v_pk_mul_f32 v[44:45], v[108:109], v[56:57]
	v_pk_fma_f32 v[42:43], v[14:15], v[42:43], v[54:55]
	v_pk_fma_f32 v[54:55], v[10:11], v[44:45], v[64:65]
	v_pk_mul_f32 v[44:45], v[100:101], v[56:57]
	v_pk_mul_f32 v[56:57], v[104:105], v[56:57]
	v_pk_fma_f32 v[44:45], v[16:17], v[44:45], v[62:63]
	v_pk_fma_f32 v[56:57], v[12:13], v[56:57], v[110:111]
	s_and_b64 vcc, exec, s[8:9]
	s_mov_b64 s[82:83], -1
	s_cbranch_vccnz .LBB0_663
	s_mov_b64 s[82:83], 0
	global_store_dwordx4 v[60:61], v[42:45], off offset:512
	global_store_dwordx4 v[60:61], v[54:57], off offset:528

; __device__ __forceinline__ uint4 pack8(const float* f) { uint4 o; o.x = pk2(f[0], f[1]); o.y = pk2(f[2], f[3]); o.z = pk2(f[4], f[5]); o.w = pk2(f[6], f[7]); return o; }
;     __device__ __forceinline__ void fused(f32x4 (&acc)[2][2][4][2], const pg8::Unit& u, int wr, int wc, int fr, int fq, LAS unsigned char* lds, int wid, int lane) const {
;     ...
;             for (int m = 0; m < 4; ++m) {
;                 const int rl = ai * 128 + wr * 64 + m * 16 + fr; const size_t off = (size_t)(u.pm * 256 + rl) * 1024 + cb;
;                 const float rsf = S[rl]; float q = 0.f;
; #pragma unroll
;                 for (int bj = 0; bj < 2; ++bj) {
;                     float xo[8]; unpack8(xold[m][bj], xo);
;                     f32x4 v0 = acc[ai][bj][m][0] * rsf * g4[bj][0], v1 = acc[ai][bj][m][1] * rsf * g4[bj][1];
;                     float xn[8];
; #pragma unroll
;                     for (int e = 0; e < 4; ++e) { xn[e] = xo[e] + v0[e]; xn[4 + e] = xo[4 + e] + v1[e]; }
;                     if (outf) { *(f32x4*)(outf + off + bj * 128) = (f32x4){xn[0], xn[1], xn[2], xn[3]}; *(f32x4*)(outf + off + bj * 128 + 4) = (f32x4){xn[4], xn[5], xn[6], xn[7]}; }
;                     else { *(uint4*)(XB + off + bj * 128) = pack8(xn); }
.LBB0_667:
	s_or_b64 exec, exec, s[82:83]
	ds_read_b32 v48, v224 offset:4736
	s_waitcnt lgkmcnt(1)
	v_add_u32_e32 v42, s2, v229
	v_ashrrev_i32_e32 v43, 31, v42
	v_lshlrev_b64 v[46:47], 10, v[42:43]
	s_nop 1
	v_lshlrev_b32_e32 v42, 16, v38
	v_and_b32_e32 v43, 0xffff0000, v38
	v_lshlrev_b32_e32 v44, 16, v39
	v_and_b32_e32 v45, 0xffff0000, v39
	v_lshlrev_b32_e32 v52, 16, v40
	v_and_b32_e32 v53, 0xffff0000, v40
	v_lshlrev_b32_e32 v54, 16, v41
	v_and_b32_e32 v55, 0xffff0000, v41
	s_waitcnt lgkmcnt(0)
	v_pk_mul_f32 v[38:39], v[94:95], v[48:49] op_sel_hi:[1,0]
	v_pk_mul_f32 v[40:41], v[96:97], v[48:49] op_sel_hi:[1,0]
	v_pk_fma_f32 v[38:39], v[22:23], v[38:39], v[42:43]
	v_pk_fma_f32 v[42:43], v[18:19], v[40:41], v[52:53]
	v_pk_mul_f32 v[40:41], v[90:91], v[48:49] op_sel_hi:[1,0]
	v_lshl_add_u64 v[50:51], v[46:47], 0, v[102:103]
	v_pk_fma_f32 v[40:41], v[24:25], v[40:41], v[44:45]
	v_pk_mul_f32 v[44:45], v[92:93], v[48:49] op_sel_hi:[1,0]
	s_mov_b64 s[82:83], -1
	v_pk_fma_f32 v[44:45], v[20:21], v[44:45], v[54:55]
	s_and_b64 vcc, exec, s[8:9]
	v_lshl_add_u64 v[52:53], v[50:51], 2, s[22:23]
	s_cbranch_vccnz .LBB0_669
	s_mov_b64 s[82:83], 0
	global_store_dwordx4 v[52:53], v[38:41], off
	global_store_dwordx4 v[52:53], v[42:45], off offset:16

; __device__ __forceinline__ uint4 pack8(const float* f) { uint4 o; o.x = pk2(f[0], f[1]); o.y = pk2(f[2], f[3]); o.z = pk2(f[4], f[5]); o.w = pk2(f[6], f[7]); return o; }
;     __device__ __forceinline__ void fused(f32x4 (&acc)[2][2][4][2], const pg8::Unit& u, int wr, int wc, int fr, int fq, LAS unsigned char* lds, int wid, int lane) const {
;     ...
;             for (int m = 0; m < 4; ++m) {
;                 const int rl = ai * 128 + wr * 64 + m * 16 + fr; const size_t off = (size_t)(u.pm * 256 + rl) * 1024 + cb;
;                 const float rsf = S[rl]; float q = 0.f;
; #pragma unroll
;                 for (int bj = 0; bj < 2; ++bj) {
;                     float xo[8]; unpack8(xold[m][bj], xo);
;                     f32x4 v0 = acc[ai][bj][m][0] * rsf * g4[bj][0], v1 = acc[ai][bj][m][1] * rsf * g4[bj][1];
;                     float xn[8];
; #pragma unroll
;                     for (int e = 0; e < 4; ++e) { xn[e] = xo[e] + v0[e]; xn[4 + e] = xo[4 + e] + v1[e]; }
;                     if (outf) { *(f32x4*)(outf + off + bj * 128) = (f32x4){xn[0], xn[1], xn[2], xn[3]}; *(f32x4*)(outf + off + bj * 128 + 4) = (f32x4){xn[4], xn[5], xn[6], xn[7]}; }
;                     else { *(uint4*)(XB + off + bj * 128) = pack8(xn); }
.LBB0_671:
	v_mov_b32_e32 v49, v48
	s_nop 1
	v_lshlrev_b32_e32 v46, 16, v34
	v_and_b32_e32 v47, 0xffff0000, v34
	v_lshlrev_b32_e32 v54, 16, v35
	v_and_b32_e32 v55, 0xffff0000, v35
	v_lshlrev_b32_e32 v56, 16, v36
	v_and_b32_e32 v57, 0xffff0000, v36
	v_lshlrev_b32_e32 v58, 16, v37
	v_and_b32_e32 v59, 0xffff0000, v37
	v_pk_mul_f32 v[34:35], v[86:87], v[48:49]
	v_pk_mul_f32 v[36:37], v[88:89], v[48:49]
	v_pk_fma_f32 v[34:35], v[14:15], v[34:35], v[46:47]
	v_pk_fma_f32 v[46:47], v[10:11], v[36:37], v[56:57]
	v_pk_mul_f32 v[36:37], v[82:83], v[48:49]
	v_pk_mul_f32 v[48:49], v[84:85], v[48:49]
	v_pk_fma_f32 v[36:37], v[16:17], v[36:37], v[54:55]
	v_pk_fma_f32 v[48:49], v[12:13], v[48:49], v[58:59]
	s_and_b64 vcc, exec, s[8:9]
	s_mov_b64 s[82:83], -1
	s_cbranch_vccnz .LBB0_673
	s_mov_b64 s[82:83], 0
	global_store_dwordx4 v[52:53], v[34:37], off offset:512
	global_store_dwordx4 v[52:53], v[46:49], off offset:528

; __device__ __forceinline__ uint4 pack8(const float* f) { uint4 o; o.x = pk2(f[0], f[1]); o.y = pk2(f[2], f[3]); o.z = pk2(f[4], f[5]); o.w = pk2(f[6], f[7]); return o; }
;     __device__ __forceinline__ void fused(f32x4 (&acc)[2][2][4][2], const pg8::Unit& u, int wr, int wc, int fr, int fq, LAS unsigned char* lds, int wid, int lane) const {
;     ...
;             for (int m = 0; m < 4; ++m) {
;                 const int rl = ai * 128 + wr * 64 + m * 16 + fr; const size_t off = (size_t)(u.pm * 256 + rl) * 1024 + cb;
;                 const float rsf = S[rl]; float q = 0.f;
; #pragma unroll
;                 for (int bj = 0; bj < 2; ++bj) {
;                     float xo[8]; unpack8(xold[m][bj], xo);
;                     f32x4 v0 = acc[ai][bj][m][0] * rsf * g4[bj][0], v1 = acc[ai][bj][m][1] * rsf * g4[bj][1];
;                     float xn[8];
; #pragma unroll
;                     for (int e = 0; e < 4; ++e) { xn[e] = xo[e] + v0[e]; xn[4 + e] = xo[4 + e] + v1[e]; }
;                     if (outf) { *(f32x4*)(outf + off + bj * 128) = (f32x4){xn[0], xn[1], xn[2], xn[3]}; *(f32x4*)(outf + off + bj * 128 + 4) = (f32x4){xn[4], xn[5], xn[6], xn[7]}; }
;                     else { *(uint4*)(XB + off + bj * 128) = pack8(xn); }
.LBB0_677:
	s_or_b64 exec, exec, s[82:83]
	s_waitcnt lgkmcnt(0)
	v_add_u32_e32 v34, s2, v227
	v_ashrrev_i32_e32 v35, 31, v34
	v_lshlrev_b64 v[36:37], 10, v[34:35]
	ds_read_b32 v34, v224 offset:4800
	s_nop 1
	v_lshlrev_b32_e32 v40, 16, v30
	v_and_b32_e32 v41, 0xffff0000, v30
	v_lshlrev_b32_e32 v42, 16, v32
	v_and_b32_e32 v43, 0xffff0000, v32
	s_waitcnt lgkmcnt(0)
	v_pk_mul_f32 v[44:45], v[78:79], v[34:35] op_sel_hi:[1,0]
	v_lshlrev_b32_e32 v30, 16, v31
	v_pk_fma_f32 v[22:23], v[22:23], v[44:45], v[40:41]
	v_pk_mul_f32 v[40:41], v[80:81], v[34:35] op_sel_hi:[1,0]
	v_and_b32_e32 v31, 0xffff0000, v31
	v_pk_fma_f32 v[18:19], v[18:19], v[40:41], v[42:43]
	v_pk_mul_f32 v[40:41], v[74:75], v[34:35] op_sel_hi:[1,0]
	v_lshl_add_u64 v[38:39], v[36:37], 0, v[102:103]
	v_lshlrev_b32_e32 v32, 16, v33
	v_and_b32_e32 v33, 0xffff0000, v33
	v_pk_fma_f32 v[24:25], v[24:25], v[40:41], v[30:31]
	v_pk_mul_f32 v[30:31], v[76:77], v[34:35] op_sel_hi:[1,0]
	s_mov_b64 s[82:83], -1
	v_pk_fma_f32 v[20:21], v[20:21], v[30:31], v[32:33]
	s_and_b64 vcc, exec, s[8:9]
	v_lshl_add_u64 v[32:33], v[38:39], 2, s[22:23]
	s_cbranch_vccnz .LBB0_679
	s_mov_b64 s[82:83], 0
	global_store_dwordx4 v[32:33], v[22:25], off
	global_store_dwordx4 v[32:33], v[18:21], off offset:16

; __device__ __forceinline__ uint4 pack8(const float* f) { uint4 o; o.x = pk2(f[0], f[1]); o.y = pk2(f[2], f[3]); o.z = pk2(f[4], f[5]); o.w = pk2(f[6], f[7]); return o; }
;     __device__ __forceinline__ void fused(f32x4 (&acc)[2][2][4][2], const pg8::Unit& u, int wr, int wc, int fr, int fq, LAS unsigned char* lds, int wid, int lane) const {
;     ...
;             for (int m = 0; m < 4; ++m) {
;                 const int rl = ai * 128 + wr * 64 + m * 16 + fr; const size_t off = (size_t)(u.pm * 256 + rl) * 1024 + cb;
;                 const float rsf = S[rl]; float q = 0.f;
; #pragma unroll
;                 for (int bj = 0; bj < 2; ++bj) {
;                     float xo[8]; unpack8(xold[m][bj], xo);
;                     f32x4 v0 = acc[ai][bj][m][0] * rsf * g4[bj][0], v1 = acc[ai][bj][m][1] * rsf * g4[bj][1];
;                     float xn[8];
; #pragma unroll
;                     for (int e = 0; e < 4; ++e) { xn[e] = xo[e] + v0[e]; xn[4 + e] = xo[4 + e] + v1[e]; }
;                     if (outf) { *(f32x4*)(outf + off + bj * 128) = (f32x4){xn[0], xn[1], xn[2], xn[3]}; *(f32x4*)(outf + off + bj * 128 + 4) = (f32x4){xn[4], xn[5], xn[6], xn[7]}; }
;                     else { *(uint4*)(XB + off + bj * 128) = pack8(xn); }
.LBB0_681:
	v_mov_b32_e32 v35, v34
	s_nop 1
	v_lshlrev_b32_e32 v36, 16, v26
	v_and_b32_e32 v37, 0xffff0000, v26
	v_pk_mul_f32 v[40:41], v[70:71], v[34:35]
	v_lshlrev_b32_e32 v26, 16, v27
	v_and_b32_e32 v27, 0xffff0000, v27
	v_lshlrev_b32_e32 v38, 16, v28
	v_and_b32_e32 v39, 0xffff0000, v28
	v_lshlrev_b32_e32 v28, 16, v29
	v_and_b32_e32 v29, 0xffff0000, v29
	v_pk_mul_f32 v[42:43], v[72:73], v[34:35]
	v_pk_fma_f32 v[14:15], v[14:15], v[40:41], v[36:37]
	v_pk_mul_f32 v[36:37], v[66:67], v[34:35]
	v_pk_mul_f32 v[34:35], v[68:69], v[34:35]
	v_pk_fma_f32 v[10:11], v[10:11], v[42:43], v[38:39]
	v_pk_fma_f32 v[16:17], v[16:17], v[36:37], v[26:27]
	v_pk_fma_f32 v[12:13], v[12:13], v[34:35], v[28:29]
	s_and_b64 vcc, exec, s[8:9]
	s_mov_b64 s[8:9], -1
	s_cbranch_vccnz .LBB0_683
	s_mov_b64 s[8:9], 0
	global_store_dwordx4 v[32:33], v[14:17], off offset:512
	global_store_dwordx4 v[32:33], v[10:13], off offset:528
